# skinny GEMM epilogue (proj too): folded-norm vector loads hoisted next to the statistics loads
# baseline (speedup 1.0000x reference)
; template <int KSPLIT, class F>
; __device__ __forceinline__ void skinny_gemm(const bf16_t* A, const bf16_t* Bt, int N, int K, const F& f, LAS unsigned char* lds, int bx, int G, int wave) {
;     ...
; #pragma unroll 16
;         for (int k = 0; k < klen; k += 32) {
;             const bf16x8 af = *(const bf16x8*)(ap + k), bf = *(const bf16x8*)(bp + k);
;             acc = __builtin_amdgcn_mfma_f32_16x16x32_bf16(bf, af, acc, 0, 0, 0);
;         }
.LBB0_1486:
	v_lshl_add_u64 v[32:33], v[28:29], 0, v[22:23]
	v_lshl_add_u64 v[34:35], v[30:31], 0, v[22:23]
	v_readlane_b32 s100, v251, 60
	s_mul_i32 s100, s100, 0x3000
	s_add_i32 s100, s100, 0x2000
	v_lshrrev_b32_e32 v202, 2, v219
	v_and_b32_e32 v203, 15, v219
	v_lshrrev_b32_e32 v201, 4, v219
	v_sub_u32_e32 v202, v202, v203
	v_lshlrev_b32_e32 v202, 11, v202
	v_and_b32_e32 v204, 3, v219
	v_xor_b32_e32 v204, v204, v201
	v_sub_u32_e32 v204, v204, v201
	v_lshl_add_u32 v202, v204, 4, v202
	v_lshrrev_b32_e32 v204, 2, v203
	v_xor_b32_e32 v204, v204, v201
	v_lshlrev_b32_e32 v200, 6, v203
	v_lshl_add_u32 v200, v204, 4, v200
	v_add_u32_e32 v200, s100, v200
	v_ashrrev_i32_e32 v203, 31, v202
	v_lshl_add_u64 v[196:197], v[202:203], 0, v[32:33]
	v_lshl_add_u64 v[198:199], v[202:203], 0, v[34:35]
	s_add_i32 m0, s100, 512
	s_nop 0
	global_load_lds_dwordx4 v[196:197], off offset:-512
	s_add_i32 m0, s100, 1024
	s_nop 0
	global_load_lds_dwordx4 v[198:199], off
	s_add_i32 m0, s100, 3008
	s_nop 0
	global_load_lds_dwordx4 v[198:199], off offset:64
	s_add_i32 m0, s100, 2496
	s_nop 0
	global_load_lds_dwordx4 v[196:197], off offset:-448
	s_add_i32 m0, s100, 4992
	s_nop 0
	global_load_lds_dwordx4 v[198:199], off offset:128
	s_add_i32 m0, s100, 4480
	s_nop 0
	global_load_lds_dwordx4 v[196:197], off offset:-384
	s_add_i32 m0, s100, 6976
	s_nop 0
	global_load_lds_dwordx4 v[198:199], off offset:192
	s_add_i32 m0, s100, 6464
	s_nop 0
	global_load_lds_dwordx4 v[196:197], off offset:-320
	s_add_i32 m0, s100, 8960
	s_nop 0
	global_load_lds_dwordx4 v[198:199], off offset:256
	s_add_i32 m0, s100, 8448
	s_nop 0
	global_load_lds_dwordx4 v[196:197], off offset:-256
	s_add_i32 m0, s100, 10944
	s_nop 0
	global_load_lds_dwordx4 v[198:199], off offset:320
	s_add_i32 m0, s100, 10432
	s_nop 0
	global_load_lds_dwordx4 v[196:197], off offset:-192
	s_waitcnt vmcnt(10)
	ds_read_b128 v[180:183], v200 offset:0
	ds_read_b128 v[184:187], v200 offset:1024
	s_waitcnt vmcnt(8)
	ds_read_b128 v[188:191], v200 offset:2048
	ds_read_b128 v[192:195], v200 offset:3072
	s_waitcnt lgkmcnt(2)
	v_mfma_f32_16x16x32_bf16 v[4:7], v[180:183], v[184:187], v[4:7]
	s_add_i32 m0, s100, 640
	s_nop 0
	global_load_lds_dwordx4 v[198:199], off offset:384
	s_add_i32 m0, s100, 128
	s_nop 0
	global_load_lds_dwordx4 v[196:197], off offset:-128
	s_waitcnt vmcnt(8)
	ds_read_b128 v[180:183], v200 offset:4096
	ds_read_b128 v[184:187], v200 offset:5120
	s_waitcnt lgkmcnt(2)
	v_mfma_f32_16x16x32_bf16 v[4:7], v[188:191], v[192:195], v[4:7]
	s_add_i32 m0, s100, 2624
	s_nop 0
	global_load_lds_dwordx4 v[198:199], off offset:448
	s_add_i32 m0, s100, 2112
	s_nop 0
	global_load_lds_dwordx4 v[196:197], off offset:-64
	s_waitcnt vmcnt(8)
	ds_read_b128 v[188:191], v200 offset:6144
	ds_read_b128 v[192:195], v200 offset:7168
	s_waitcnt lgkmcnt(2)
	v_mfma_f32_16x16x32_bf16 v[4:7], v[180:183], v[184:187], v[4:7]
	s_add_i32 m0, s100, 4608
	s_nop 0
	global_load_lds_dwordx4 v[198:199], off offset:512
	s_add_i32 m0, s100, 4096
	s_nop 0
	global_load_lds_dwordx4 v[196:197], off
	s_waitcnt vmcnt(8)
	ds_read_b128 v[180:183], v200 offset:8192
	ds_read_b128 v[184:187], v200 offset:9216
	s_waitcnt lgkmcnt(2)
	v_mfma_f32_16x16x32_bf16 v[4:7], v[188:191], v[192:195], v[4:7]
	s_add_i32 m0, s100, 6592
	s_nop 0
	global_load_lds_dwordx4 v[198:199], off offset:576
	s_add_i32 m0, s100, 6080
	s_nop 0
	global_load_lds_dwordx4 v[196:197], off offset:64
	s_waitcnt vmcnt(8)
	ds_read_b128 v[188:191], v200 offset:10240
	ds_read_b128 v[192:195], v200 offset:11264
	s_waitcnt lgkmcnt(2)
	v_mfma_f32_16x16x32_bf16 v[4:7], v[180:183], v[184:187], v[4:7]
	s_add_i32 m0, s100, 8576
	s_nop 0
	global_load_lds_dwordx4 v[198:199], off offset:640
	s_add_i32 m0, s100, 8064
	s_nop 0
	global_load_lds_dwordx4 v[196:197], off offset:128
	s_waitcnt vmcnt(8)
	ds_read_b128 v[180:183], v200 offset:0
	ds_read_b128 v[184:187], v200 offset:1024
	s_waitcnt lgkmcnt(2)
	v_mfma_f32_16x16x32_bf16 v[4:7], v[188:191], v[192:195], v[4:7]
	s_add_i32 m0, s100, 10560
	s_nop 0
	global_load_lds_dwordx4 v[198:199], off offset:704
	s_add_i32 m0, s100, 10048
	s_nop 0
	global_load_lds_dwordx4 v[196:197], off offset:192
	s_waitcnt vmcnt(8)
	ds_read_b128 v[188:191], v200 offset:2048
	ds_read_b128 v[192:195], v200 offset:3072
	s_waitcnt lgkmcnt(2)
	v_mfma_f32_16x16x32_bf16 v[4:7], v[180:183], v[184:187], v[4:7]
	s_add_i32 m0, s100, 256
	s_nop 0
	global_load_lds_dwordx4 v[198:199], off offset:768
	s_add_i32 m0, s100, -256
	s_nop 0
	global_load_lds_dwordx4 v[196:197], off offset:256
	s_waitcnt vmcnt(8)
	ds_read_b128 v[180:183], v200 offset:4096
	ds_read_b128 v[184:187], v200 offset:5120
	s_waitcnt lgkmcnt(2)
	v_mfma_f32_16x16x32_bf16 v[4:7], v[188:191], v[192:195], v[4:7]
	s_add_i32 m0, s100, 2240
	s_nop 0
	global_load_lds_dwordx4 v[198:199], off offset:832
	s_add_i32 m0, s100, 1728
	s_nop 0
	global_load_lds_dwordx4 v[196:197], off offset:320
	s_waitcnt vmcnt(8)
	ds_read_b128 v[188:191], v200 offset:6144
	ds_read_b128 v[192:195], v200 offset:7168
	s_waitcnt lgkmcnt(2)
	v_mfma_f32_16x16x32_bf16 v[4:7], v[180:183], v[184:187], v[4:7]
	s_add_i32 m0, s100, 4224
	s_nop 0
	global_load_lds_dwordx4 v[198:199], off offset:896
	s_add_i32 m0, s100, 3712
	s_nop 0
	global_load_lds_dwordx4 v[196:197], off offset:384
	s_waitcnt vmcnt(8)
	ds_read_b128 v[180:183], v200 offset:8192
	ds_read_b128 v[184:187], v200 offset:9216
	s_waitcnt lgkmcnt(2)
	v_mfma_f32_16x16x32_bf16 v[4:7], v[188:191], v[192:195], v[4:7]
	s_add_i32 m0, s100, 6208
	s_nop 0
	global_load_lds_dwordx4 v[198:199], off offset:960
	s_add_i32 m0, s100, 5696
	s_nop 0
	global_load_lds_dwordx4 v[196:197], off offset:448
	s_waitcnt vmcnt(8)
; template <int KSPLIT, class F>
; __device__ __forceinline__ void skinny_gemm(const bf16_t* A, const bf16_t* Bt, int N, int K, const F& f, LAS unsigned char* lds, int bx, int G, int wave) {
;     ...
; #pragma unroll 16
;         for (int k = 0; k < klen; k += 32) {
;             const bf16x8 af = *(const bf16x8*)(ap + k), bf = *(const bf16x8*)(bp + k);
;             acc = __builtin_amdgcn_mfma_f32_16x16x32_bf16(bf, af, acc, 0, 0, 0);
;         }
	ds_read_b128 v[188:191], v200 offset:10240
	ds_read_b128 v[192:195], v200 offset:11264
	s_waitcnt lgkmcnt(2)
	v_mfma_f32_16x16x32_bf16 v[4:7], v[180:183], v[184:187], v[4:7]
	s_add_i32 m0, s100, 7680
	s_nop 0
	global_load_lds_dwordx4 v[196:197], off offset:512
	s_add_i32 m0, s100, 8192
	s_nop 0
	global_load_lds_dwordx4 v[198:199], off offset:1024
	s_waitcnt vmcnt(8)
	ds_read_b128 v[180:183], v200 offset:0
	ds_read_b128 v[184:187], v200 offset:1024
	s_waitcnt lgkmcnt(2)
	v_mfma_f32_16x16x32_bf16 v[4:7], v[188:191], v[192:195], v[4:7]
	s_add_i32 m0, s100, 10176
	s_nop 0
	global_load_lds_dwordx4 v[198:199], off offset:1088
	s_add_i32 m0, s100, 9664
	s_nop 0
	global_load_lds_dwordx4 v[196:197], off offset:576
	s_waitcnt vmcnt(8)
	ds_read_b128 v[188:191], v200 offset:2048
	ds_read_b128 v[192:195], v200 offset:3072
	s_waitcnt lgkmcnt(2)
	v_mfma_f32_16x16x32_bf16 v[4:7], v[180:183], v[184:187], v[4:7]
	s_add_i32 m0, s100, -128
	s_nop 0
	global_load_lds_dwordx4 v[198:199], off offset:1152
	s_add_i32 m0, s100, -640
	s_nop 0
	global_load_lds_dwordx4 v[196:197], off offset:640
	s_waitcnt vmcnt(8)
	ds_read_b128 v[180:183], v200 offset:4096
	ds_read_b128 v[184:187], v200 offset:5120
	s_waitcnt lgkmcnt(2)
	v_mfma_f32_16x16x32_bf16 v[4:7], v[188:191], v[192:195], v[4:7]
	s_add_i32 m0, s100, 1856
	s_nop 0
	global_load_lds_dwordx4 v[198:199], off offset:1216
	s_add_i32 m0, s100, 1344
	s_nop 0
	global_load_lds_dwordx4 v[196:197], off offset:704
	s_waitcnt vmcnt(8)
	ds_read_b128 v[188:191], v200 offset:6144
	ds_read_b128 v[192:195], v200 offset:7168
	s_waitcnt lgkmcnt(2)
	v_mfma_f32_16x16x32_bf16 v[4:7], v[180:183], v[184:187], v[4:7]
	s_add_i32 m0, s100, 3840
	s_nop 0
	global_load_lds_dwordx4 v[198:199], off offset:1280
	s_add_i32 m0, s100, 3328
	s_nop 0
	global_load_lds_dwordx4 v[196:197], off offset:768
	s_waitcnt vmcnt(8)
	ds_read_b128 v[180:183], v200 offset:8192
	ds_read_b128 v[184:187], v200 offset:9216
	s_waitcnt lgkmcnt(2)
	v_mfma_f32_16x16x32_bf16 v[4:7], v[188:191], v[192:195], v[4:7]
	s_add_i32 m0, s100, 5824
	s_nop 0
	global_load_lds_dwordx4 v[198:199], off offset:1344
	s_add_i32 m0, s100, 5312
	s_nop 0
	global_load_lds_dwordx4 v[196:197], off offset:832
	s_waitcnt vmcnt(8)
	ds_read_b128 v[188:191], v200 offset:10240
	ds_read_b128 v[192:195], v200 offset:11264
	s_waitcnt lgkmcnt(2)
	v_mfma_f32_16x16x32_bf16 v[4:7], v[180:183], v[184:187], v[4:7]
	s_add_i32 m0, s100, 7808
	s_nop 0
	global_load_lds_dwordx4 v[198:199], off offset:1408
	s_add_i32 m0, s100, 7296
	s_nop 0
	global_load_lds_dwordx4 v[196:197], off offset:896
	s_waitcnt vmcnt(8)
	ds_read_b128 v[180:183], v200 offset:0
	ds_read_b128 v[184:187], v200 offset:1024
	s_waitcnt lgkmcnt(2)
	v_mfma_f32_16x16x32_bf16 v[4:7], v[188:191], v[192:195], v[4:7]
	s_add_i32 m0, s100, 9792
	s_nop 0
	global_load_lds_dwordx4 v[198:199], off offset:1472
	s_add_i32 m0, s100, 9280
	s_nop 0
	global_load_lds_dwordx4 v[196:197], off offset:960
	s_waitcnt vmcnt(8)
	ds_read_b128 v[188:191], v200 offset:2048
	ds_read_b128 v[192:195], v200 offset:3072
	s_waitcnt lgkmcnt(2)
	v_mfma_f32_16x16x32_bf16 v[4:7], v[180:183], v[184:187], v[4:7]
	s_add_i32 m0, s100, -512
	s_nop 0
	global_load_lds_dwordx4 v[198:199], off offset:1536
	s_add_i32 m0, s100, -1024
	s_nop 0
	global_load_lds_dwordx4 v[196:197], off offset:1024
	s_waitcnt vmcnt(8)
	ds_read_b128 v[180:183], v200 offset:4096
	ds_read_b128 v[184:187], v200 offset:5120
	s_waitcnt lgkmcnt(2)
	v_mfma_f32_16x16x32_bf16 v[4:7], v[188:191], v[192:195], v[4:7]
	s_add_i32 m0, s100, 1472
	s_nop 0
	global_load_lds_dwordx4 v[198:199], off offset:1600
	s_add_i32 m0, s100, 960
	s_nop 0
	global_load_lds_dwordx4 v[196:197], off offset:1088
	s_waitcnt vmcnt(8)
	ds_read_b128 v[188:191], v200 offset:6144
	ds_read_b128 v[192:195], v200 offset:7168
	s_waitcnt lgkmcnt(2)
	v_mfma_f32_16x16x32_bf16 v[4:7], v[180:183], v[184:187], v[4:7]
	s_add_i32 m0, s100, 3456
	s_nop 0
	global_load_lds_dwordx4 v[198:199], off offset:1664
	s_add_i32 m0, s100, 2944
	s_nop 0
	global_load_lds_dwordx4 v[196:197], off offset:1152
	s_waitcnt vmcnt(8)
	ds_read_b128 v[180:183], v200 offset:8192
	ds_read_b128 v[184:187], v200 offset:9216
	s_waitcnt lgkmcnt(2)
	v_mfma_f32_16x16x32_bf16 v[4:7], v[188:191], v[192:195], v[4:7]
	s_add_i32 m0, s100, 5440
	s_nop 0
	global_load_lds_dwordx4 v[198:199], off offset:1728
	s_add_i32 m0, s100, 4928
	s_nop 0
	global_load_lds_dwordx4 v[196:197], off offset:1216
	s_waitcnt vmcnt(8)
	ds_read_b128 v[188:191], v200 offset:10240
	ds_read_b128 v[192:195], v200 offset:11264
	s_waitcnt lgkmcnt(2)
	v_mfma_f32_16x16x32_bf16 v[4:7], v[180:183], v[184:187], v[4:7]
	s_add_i32 m0, s100, 7424
	s_nop 0
	global_load_lds_dwordx4 v[198:199], off offset:1792
	s_add_i32 m0, s100, 6912
	s_nop 0
	global_load_lds_dwordx4 v[196:197], off offset:1280
	s_waitcnt vmcnt(8)
	ds_read_b128 v[180:183], v200 offset:0
	ds_read_b128 v[184:187], v200 offset:1024
	s_waitcnt lgkmcnt(2)
	v_mfma_f32_16x16x32_bf16 v[4:7], v[188:191], v[192:195], v[4:7]
	s_add_i32 m0, s100, 9408
	s_nop 0
	global_load_lds_dwordx4 v[198:199], off offset:1856
	s_add_i32 m0, s100, 8896
	s_nop 0
	global_load_lds_dwordx4 v[196:197], off offset:1344
	s_waitcnt vmcnt(8)
	ds_read_b128 v[188:191], v200 offset:2048
	ds_read_b128 v[192:195], v200 offset:3072
	s_waitcnt lgkmcnt(2)
	v_mfma_f32_16x16x32_bf16 v[4:7], v[180:183], v[184:187], v[4:7]
	s_add_i32 m0, s100, -896
	s_nop 0
	global_load_lds_dwordx4 v[198:199], off offset:1920
	s_add_i32 m0, s100, -1408
	s_nop 0
	global_load_lds_dwordx4 v[196:197], off offset:1408
	s_waitcnt vmcnt(8)
	ds_read_b128 v[180:183], v200 offset:4096
	ds_read_b128 v[184:187], v200 offset:5120
	s_waitcnt lgkmcnt(2)
	v_mfma_f32_16x16x32_bf16 v[4:7], v[188:191], v[192:195], v[4:7]
	s_add_i32 m0, s100, 1088
	s_nop 0
	global_load_lds_dwordx4 v[198:199], off offset:1984
	s_add_i32 m0, s100, 576
	s_nop 0
	global_load_lds_dwordx4 v[196:197], off offset:1472
	s_waitcnt vmcnt(8)
	ds_read_b128 v[188:191], v200 offset:6144
	ds_read_b128 v[192:195], v200 offset:7168
	s_waitcnt lgkmcnt(2)
	v_mfma_f32_16x16x32_bf16 v[4:7], v[180:183], v[184:187], v[4:7]
	s_waitcnt vmcnt(6)
	ds_read_b128 v[180:183], v200 offset:8192
	ds_read_b128 v[184:187], v200 offset:9216
	s_waitcnt lgkmcnt(2)
	v_mfma_f32_16x16x32_bf16 v[4:7], v[188:191], v[192:195], v[4:7]
	s_waitcnt vmcnt(4)
	ds_read_b128 v[188:191], v200 offset:10240
	ds_read_b128 v[192:195], v200 offset:11264
	s_waitcnt lgkmcnt(2)
	v_mfma_f32_16x16x32_bf16 v[4:7], v[180:183], v[184:187], v[4:7]
	s_waitcnt vmcnt(2)
	ds_read_b128 v[180:183], v200 offset:0
	ds_read_b128 v[184:187], v200 offset:1024
	s_waitcnt lgkmcnt(2)
	v_mfma_f32_16x16x32_bf16 v[4:7], v[188:191], v[192:195], v[4:7]
	s_waitcnt vmcnt(0)
	ds_read_b128 v[188:191], v200 offset:2048
	ds_read_b128 v[192:195], v200 offset:3072
	s_waitcnt lgkmcnt(2)
	v_mfma_f32_16x16x32_bf16 v[4:7], v[180:183], v[184:187], v[4:7]
	s_waitcnt lgkmcnt(0)
	v_mfma_f32_16x16x32_bf16 v[4:7], v[188:191], v[192:195], v[4:7]
	s_barrier
; __device__ __forceinline__ void stats_sk(const float* sts, int row, int fq, float& mu, float& rs) {
;     const f32x4* p = (const f32x4*)(sts + (size_t)(row - MP) * 128 + fq * 32);
;     float s1 = 0.f, s2 = 0.f;
; #pragma unroll
;     for (int i = 0; i < 8; ++i) { const f32x4 a = p[i]; s1 += a.x + a.z; s2 += a.y + a.w; }
;     s1 += __shfl_xor(s1, 16); s2 += __shfl_xor(s2, 16); s1 += __shfl_xor(s1, 32); s2 += __shfl_xor(s2, 32);
;     mu = s1 * (1.f / DM); rs = __builtin_amdgcn_rsqf(fmaxf(s2 * (1.f / DM) - mu * mu, 0.f) + LN_EPS);
;     __device__ __forceinline__ void sk(int row, int col, f32x4 v, int fq) const {
;         if (fold) { float mu, rs; stats_sk(sts, row, fq, mu, rs); const f32x4 c1v = *(const f32x4*)(c1 + col), c2v = *(const f32x4*)(c2 + col); v = (v - c1v * mu) * rs + c2v; }
;         float d1 = 0.f, d2 = 0.f; f(row, col, v, fq, d1, d2);
	s_nop 0
	v_lshl_add_u32 v28, s2, 4, v3
	s_andn2_b64 vcc, exec, s[96:97]
	s_cbranch_vccnz .LBB0_1489
	global_load_dwordx4 v[30:33], v[0:1], off offset:48
	global_load_dwordx4 v[34:37], v[0:1], off offset:32
	global_load_dwordx4 v[38:41], v[0:1], off offset:16
	global_load_dwordx4 v[42:45], v[0:1], off
	global_load_dwordx4 v[46:49], v[0:1], off offset:112
	global_load_dwordx4 v[50:53], v[0:1], off offset:96
	global_load_dwordx4 v[54:57], v[0:1], off offset:80
	global_load_dwordx4 v[58:61], v[0:1], off offset:64
	v_mov_b32_e32 v192, v28
	v_ashrrev_i32_e32 v193, 31, v28
	v_lshlrev_b64 v[192:193], 2, v[192:193]
	v_readlane_b32 s101, v250, 35
	s_nop 1
	v_mov_b32_e32 v184, s101
	v_readlane_b32 s101, v250, 36
	s_nop 1
	v_mov_b32_e32 v185, s101
	v_lshl_add_u64 v[184:185], v[184:185], 0, v[192:193]
	v_lshl_add_u64 v[188:189], s[64:65], 0, v[192:193]
	global_load_dwordx4 v[184:187], v[184:185], off
	s_nop 0
	global_load_dwordx4 v[188:191], v[188:189], off
	v_and_b32_e32 v29, 64, v219
	v_xor_b32_e32 v25, 16, v219
	v_add_u32_e32 v29, 64, v29
	v_cmp_lt_i32_e32 vcc, v25, v29
	v_xor_b32_e32 v62, 32, v219
	v_readlane_b32 s0, v250, 35
	v_cndmask_b32_e32 v25, v219, v25, vcc
	v_lshlrev_b32_e32 v25, 2, v25
	v_cmp_lt_i32_e32 vcc, v62, v29
	v_readlane_b32 s1, v250, 36
	s_waitcnt vmcnt(9)
	v_pk_add_f32 v[30:31], v[30:31], v[32:33]
	s_waitcnt vmcnt(8)
	v_pk_add_f32 v[34:35], v[34:35], v[36:37]
	s_waitcnt vmcnt(7)
	v_pk_add_f32 v[38:39], v[38:39], v[40:41]
	s_waitcnt vmcnt(6)
	v_pk_add_f32 v[42:43], v[42:43], v[44:45]
	v_cndmask_b32_e32 v29, v219, v62, vcc
	v_pk_add_f32 v[42:43], v[42:43], 0 op_sel_hi:[1,0]
	v_lshlrev_b32_e32 v29, 2, v29
	v_pk_add_f32 v[38:39], v[42:43], v[38:39]
	s_waitcnt vmcnt(2)
	v_pk_add_f32 v[32:33], v[58:59], v[60:61]
	v_pk_add_f32 v[34:35], v[38:39], v[34:35]
	s_nop 0
	v_pk_add_f32 v[30:31], v[34:35], v[30:31]
	s_nop 0
	v_pk_add_f32 v[30:31], v[30:31], v[32:33]
	v_pk_add_f32 v[32:33], v[54:55], v[56:57]
	s_nop 0
	v_pk_add_f32 v[30:31], v[30:31], v[32:33]
	v_pk_add_f32 v[32:33], v[50:51], v[52:53]
	s_nop 0
	v_pk_add_f32 v[30:31], v[30:31], v[32:33]
	v_pk_add_f32 v[32:33], v[46:47], v[48:49]
	s_nop 0
	v_pk_add_f32 v[30:31], v[30:31], v[32:33]
	ds_bpermute_b32 v32, v25, v30
	ds_bpermute_b32 v33, v25, v31
	s_waitcnt lgkmcnt(0)
	v_pk_add_f32 v[30:31], v[30:31], v[32:33]
	ds_bpermute_b32 v32, v29, v30
	ds_bpermute_b32 v33, v29, v31
	v_ashrrev_i32_e32 v29, 31, v28
	v_lshlrev_b64 v[38:39], 2, v[28:29]
	v_lshl_add_u64 v[34:35], s[0:1], 0, v[38:39]
	s_waitcnt vmcnt(0)
	v_mov_b32_e32 v34, v184
	v_mov_b32_e32 v35, v185
	v_mov_b32_e32 v36, v186
	v_mov_b32_e32 v37, v187
	v_lshl_add_u64 v[38:39], s[64:65], 0, v[38:39]
	v_mov_b32_e32 v38, v188
	v_mov_b32_e32 v39, v189
	v_mov_b32_e32 v40, v190
	v_mov_b32_e32 v41, v191
	s_waitcnt lgkmcnt(0)
	v_pk_add_f32 v[30:31], v[30:31], v[32:33]
	s_nop 0
	v_pk_mul_f32 v[32:33], v[30:31], s[82:83] op_sel_hi:[1,0]
	s_nop 0
	v_fma_f32 v25, -v32, v32, v33
	v_max_f32_e32 v25, 0, v25
	v_add_f32_e32 v25, 0x3727c5ac, v25
	v_rsq_f32_e32 v30, v25
	s_waitcnt vmcnt(1)
	v_pk_fma_f32 v[4:5], v[34:35], v[32:33], v[4:5] op_sel_hi:[1,0,1] neg_lo:[1,0,0] neg_hi:[1,0,0]
	v_xor_b32_e32 v35, 0x80000000, v37
	v_xor_b32_e32 v34, 0x80000000, v36
	v_pk_fma_f32 v[6:7], v[34:35], v[32:33], v[6:7] op_sel_hi:[1,0,1]
	s_waitcnt vmcnt(0)
	v_pk_fma_f32 v[4:5], v[4:5], v[30:31], v[38:39] op_sel_hi:[1,0,1]
	v_pk_fma_f32 v[6:7], v[6:7], v[30:31], v[40:41] op_sel_hi:[1,0,1]
